# merge scratch tiles use a lane-contiguous layout (same bytes, same owner lane): 256-byte runs per 16 lanes instead of 64-byte row pieces
# speedup vs baseline: 1.1037x; 1.0165x over previous
.LBB0_1056:
	s_add_i32 s56, s28, 2
	s_add_u32 s29, s24, 0xfffc0080
	s_addc_u32 s30, s25, -1
	s_add_i32 s57, 0, 0x10000
	v_add_u32_e32 v142, s57, v216
	ds_read_b128 v[130:133], v142
	ds_read_b128 v[134:137], v142 offset:1024
	ds_read_b128 v[138:141], v142 offset:2048
	ds_read_b128 v[142:145], v142 offset:3072
	s_cmp_eq_u32 s17, s28
	s_cselect_b32 s28, s22, s19
	s_cselect_b32 s31, s21, s30
	s_cselect_b32 s30, s20, s29
	s_cselect_b32 s29, s23, s27
	v_lshl_add_u64 v[178:179], s[24:25], 0, v[204:205]
	s_add_i32 m0, s39, 0xc000
	ds_read_b128 v[146:149], v217
	ds_read_b128 v[150:153], v217 offset:1024
	ds_read_b128 v[154:157], v217 offset:2048
	ds_read_b128 v[158:161], v217 offset:3072
	ds_read_b128 v[162:165], v217 offset:4096
	ds_read_b128 v[166:169], v217 offset:5120
	ds_read_b128 v[170:173], v217 offset:6144
	ds_read_b128 v[174:177], v217 offset:7168
	global_load_lds_dwordx4 v[178:179], off
	v_lshl_add_u64 v[178:179], s[24:25], 0, v[206:207]
	s_add_i32 m0, s39, 0xe000
	s_nop 0
	global_load_lds_dwordx4 v[178:179], off
	s_waitcnt lgkmcnt(8)
	s_barrier
	s_waitcnt lgkmcnt(0)
	s_setprio 1
	s_waitcnt lgkmcnt(0)
	v_mfma_f32_16x16x32_bf16 v[126:129], v[130:133], v[146:149], v[126:129]
	v_mfma_f32_16x16x32_bf16 v[122:125], v[138:141], v[146:149], v[122:125]
	v_mfma_f32_16x16x32_bf16 v[118:121], v[130:133], v[154:157], v[118:121]
	v_mfma_f32_16x16x32_bf16 v[114:117], v[138:141], v[154:157], v[114:117]
	v_mfma_f32_16x16x32_bf16 v[102:105], v[130:133], v[162:165], v[102:105]
	v_mfma_f32_16x16x32_bf16 v[98:101], v[138:141], v[162:165], v[98:101]
	v_mfma_f32_16x16x32_bf16 v[86:89], v[130:133], v[170:173], v[86:89]
	v_mfma_f32_16x16x32_bf16 v[82:85], v[138:141], v[170:173], v[82:85]
	v_mfma_f32_16x16x32_bf16 v[126:129], v[134:137], v[150:153], v[126:129]
	v_mfma_f32_16x16x32_bf16 v[122:125], v[142:145], v[150:153], v[122:125]
	v_mfma_f32_16x16x32_bf16 v[118:121], v[134:137], v[158:161], v[118:121]
	v_mfma_f32_16x16x32_bf16 v[114:117], v[142:145], v[158:161], v[114:117]
	v_mfma_f32_16x16x32_bf16 v[102:105], v[134:137], v[166:169], v[102:105]
	v_mfma_f32_16x16x32_bf16 v[98:101], v[142:145], v[166:169], v[98:101]
	v_mfma_f32_16x16x32_bf16 v[86:89], v[134:137], v[174:177], v[86:89]
	v_mfma_f32_16x16x32_bf16 v[82:85], v[142:145], v[174:177], v[82:85]
	s_setprio 0
	s_barrier
	s_add_i32 s60, 0, 0x14000
	s_add_i32 s57, s57, s38
	v_add_u32_e32 v190, s60, v216
	v_lshl_add_u64 v[208:209], s[28:29], 0, v[48:49]
	s_mov_b32 m0, s57
	ds_read_b128 v[178:181], v190
	ds_read_b128 v[182:185], v190 offset:1024
	ds_read_b128 v[186:189], v190 offset:2048
	ds_read_b128 v[190:193], v190 offset:3072
	global_load_lds_dwordx4 v[208:209], off
	v_lshl_add_u64 v[210:211], s[28:29], 0, v[202:203]
	s_add_i32 m0, s57, 0x2000
	s_nop 0
	global_load_lds_dwordx4 v[210:211], off
	s_barrier
	s_waitcnt lgkmcnt(0)
	s_setprio 1
	s_waitcnt lgkmcnt(0)
	v_mfma_f32_16x16x32_bf16 v[110:113], v[178:181], v[146:149], v[110:113]
	v_mfma_f32_16x16x32_bf16 v[106:109], v[186:189], v[146:149], v[106:109]
	v_mfma_f32_16x16x32_bf16 v[94:97], v[178:181], v[154:157], v[94:97]
	v_mfma_f32_16x16x32_bf16 v[90:93], v[186:189], v[154:157], v[90:93]
	v_mfma_f32_16x16x32_bf16 v[78:81], v[178:181], v[162:165], v[78:81]
	v_mfma_f32_16x16x32_bf16 v[74:77], v[186:189], v[162:165], v[74:77]
	v_mfma_f32_16x16x32_bf16 v[70:73], v[178:181], v[170:173], v[70:73]
	v_mfma_f32_16x16x32_bf16 v[66:69], v[186:189], v[170:173], v[66:69]
	v_mfma_f32_16x16x32_bf16 v[110:113], v[182:185], v[150:153], v[110:113]
	v_mfma_f32_16x16x32_bf16 v[106:109], v[190:193], v[150:153], v[106:109]
	v_mfma_f32_16x16x32_bf16 v[94:97], v[182:185], v[158:161], v[94:97]
	v_mfma_f32_16x16x32_bf16 v[90:93], v[190:193], v[158:161], v[90:93]
	v_mfma_f32_16x16x32_bf16 v[78:81], v[182:185], v[166:169], v[78:81]
	v_mfma_f32_16x16x32_bf16 v[74:77], v[190:193], v[166:169], v[74:77]
	v_mfma_f32_16x16x32_bf16 v[70:73], v[182:185], v[174:177], v[70:73]
	v_mfma_f32_16x16x32_bf16 v[66:69], v[190:193], v[174:177], v[66:69]
	s_setprio 0
	s_mov_b32 m0, s39
	v_lshl_add_u64 v[212:213], s[30:31], 0, v[198:199]
	s_barrier
	ds_read_b128 v[146:149], v217 offset:16384
	ds_read_b128 v[150:153], v217 offset:17408
	ds_read_b128 v[154:157], v217 offset:18432
	ds_read_b128 v[158:161], v217 offset:19456
	ds_read_b128 v[162:165], v217 offset:20480
	ds_read_b128 v[166:169], v217 offset:21504
	ds_read_b128 v[170:173], v217 offset:22528
	ds_read_b128 v[174:177], v217 offset:23552
	global_load_lds_dwordx4 v[212:213], off
	v_lshl_add_u64 v[218:219], s[30:31], 0, v[200:201]
	s_mov_b32 m0, s40
	s_nop 0
	global_load_lds_dwordx4 v[218:219], off
	s_barrier
	s_waitcnt lgkmcnt(0)
	s_setprio 1
	s_waitcnt lgkmcnt(0)
	v_mfma_f32_16x16x32_bf16 v[62:65], v[130:133], v[146:149], v[62:65]
	v_mfma_f32_16x16x32_bf16 v[58:61], v[138:141], v[146:149], v[58:61]
	v_mfma_f32_16x16x32_bf16 v[54:57], v[130:133], v[154:157], v[54:57]
	v_mfma_f32_16x16x32_bf16 v[50:53], v[138:141], v[154:157], v[50:53]
	v_mfma_f32_16x16x32_bf16 v[36:39], v[130:133], v[162:165], v[36:39]
	v_mfma_f32_16x16x32_bf16 v[32:35], v[138:141], v[162:165], v[32:35]
	v_mfma_f32_16x16x32_bf16 v[20:23], v[130:133], v[170:173], v[20:23]
	v_mfma_f32_16x16x32_bf16 v[16:19], v[138:141], v[170:173], v[16:19]
	v_mfma_f32_16x16x32_bf16 v[62:65], v[134:137], v[150:153], v[62:65]
	v_mfma_f32_16x16x32_bf16 v[58:61], v[142:145], v[150:153], v[58:61]
	v_mfma_f32_16x16x32_bf16 v[54:57], v[134:137], v[158:161], v[54:57]
	v_mfma_f32_16x16x32_bf16 v[50:53], v[142:145], v[158:161], v[50:53]
	v_mfma_f32_16x16x32_bf16 v[36:39], v[134:137], v[166:169], v[36:39]
	v_mfma_f32_16x16x32_bf16 v[32:35], v[142:145], v[166:169], v[32:35]
	v_mfma_f32_16x16x32_bf16 v[20:23], v[134:137], v[174:177], v[20:23]
	v_mfma_f32_16x16x32_bf16 v[16:19], v[142:145], v[174:177], v[16:19]
	s_setprio 0
	s_barrier
	s_add_u32 s58, s28, 0x40000
	s_addc_u32 s59, s29, 0
	s_add_i32 s57, s60, s38
	v_lshl_add_u64 v[130:131], s[58:59], 0, v[48:49]
	s_mov_b32 m0, s57
	s_nop 0
	global_load_lds_dwordx4 v[130:131], off
	v_lshl_add_u64 v[130:131], s[58:59], 0, v[202:203]
	s_add_i32 m0, s57, 0x2000
	s_nop 0
	global_load_lds_dwordx4 v[130:131], off
	s_waitcnt vmcnt(6)
	s_barrier
	s_setprio 1
	v_mfma_f32_16x16x32_bf16 v[44:47], v[178:181], v[146:149], v[44:47]
	v_mfma_f32_16x16x32_bf16 v[40:43], v[186:189], v[146:149], v[40:43]
	v_mfma_f32_16x16x32_bf16 v[28:31], v[178:181], v[154:157], v[28:31]
	v_mfma_f32_16x16x32_bf16 v[24:27], v[186:189], v[154:157], v[24:27]
	v_mfma_f32_16x16x32_bf16 v[12:15], v[178:181], v[162:165], v[12:15]
	v_mfma_f32_16x16x32_bf16 v[8:11], v[186:189], v[162:165], v[8:11]
	v_mfma_f32_16x16x32_bf16 v[4:7], v[178:181], v[170:173], v[4:7]
	v_mfma_f32_16x16x32_bf16 v[0:3], v[186:189], v[170:173], v[0:3]
	v_mfma_f32_16x16x32_bf16 v[44:47], v[182:185], v[150:153], v[44:47]
	v_mfma_f32_16x16x32_bf16 v[40:43], v[190:193], v[150:153], v[40:43]
	v_mfma_f32_16x16x32_bf16 v[28:31], v[182:185], v[158:161], v[28:31]
	v_mfma_f32_16x16x32_bf16 v[24:27], v[190:193], v[158:161], v[24:27]
	v_mfma_f32_16x16x32_bf16 v[12:15], v[182:185], v[166:169], v[12:15]
	v_mfma_f32_16x16x32_bf16 v[8:11], v[190:193], v[166:169], v[8:11]
	v_mfma_f32_16x16x32_bf16 v[4:7], v[182:185], v[174:177], v[4:7]
	v_mfma_f32_16x16x32_bf16 v[0:3], v[190:193], v[174:177], v[0:3]
	s_setprio 0
	s_add_i32 s57, 0, 0x18000
	v_add_u32_e32 v142, s57, v216
	s_barrier
	ds_read_b128 v[130:133], v142
	ds_read_b128 v[134:137], v142 offset:1024
	ds_read_b128 v[138:141], v142 offset:2048
	ds_read_b128 v[142:145], v142 offset:3072
	s_add_u32 s30, s30, 0x40000
	s_addc_u32 s31, s31, 0
	s_mov_b32 m0, s41
	v_lshl_add_u64 v[178:179], s[30:31], 0, v[198:199]
	ds_read_b128 v[146:149], v217 offset:32768
	ds_read_b128 v[150:153], v217 offset:33792
	ds_read_b128 v[154:157], v217 offset:34816
	ds_read_b128 v[158:161], v217 offset:35840
	ds_read_b128 v[162:165], v217 offset:36864
	ds_read_b128 v[166:169], v217 offset:37888
	ds_read_b128 v[170:173], v217 offset:38912
	ds_read_b128 v[174:177], v217 offset:39936
	global_load_lds_dwordx4 v[178:179], off
	v_lshl_add_u64 v[178:179], s[30:31], 0, v[200:201]
	s_mov_b32 m0, s42
	s_nop 0
	global_load_lds_dwordx4 v[178:179], off
	s_waitcnt lgkmcnt(8)
	s_barrier
	s_waitcnt lgkmcnt(0)
	s_setprio 1
	s_waitcnt lgkmcnt(0)
	v_mfma_f32_16x16x32_bf16 v[126:129], v[130:133], v[146:149], v[126:129]
	v_mfma_f32_16x16x32_bf16 v[122:125], v[138:141], v[146:149], v[122:125]
	v_mfma_f32_16x16x32_bf16 v[118:121], v[130:133], v[154:157], v[118:121]
	v_mfma_f32_16x16x32_bf16 v[114:117], v[138:141], v[154:157], v[114:117]
	v_mfma_f32_16x16x32_bf16 v[102:105], v[130:133], v[162:165], v[102:105]
	v_mfma_f32_16x16x32_bf16 v[98:101], v[138:141], v[162:165], v[98:101]
	v_mfma_f32_16x16x32_bf16 v[86:89], v[130:133], v[170:173], v[86:89]
	v_mfma_f32_16x16x32_bf16 v[82:85], v[138:141], v[170:173], v[82:85]
	v_mfma_f32_16x16x32_bf16 v[126:129], v[134:137], v[150:153], v[126:129]
	v_mfma_f32_16x16x32_bf16 v[122:125], v[142:145], v[150:153], v[122:125]
	v_mfma_f32_16x16x32_bf16 v[118:121], v[134:137], v[158:161], v[118:121]
	v_mfma_f32_16x16x32_bf16 v[114:117], v[142:145], v[158:161], v[114:117]
	v_mfma_f32_16x16x32_bf16 v[102:105], v[134:137], v[166:169], v[102:105]
	v_mfma_f32_16x16x32_bf16 v[98:101], v[142:145], v[166:169], v[98:101]
	v_mfma_f32_16x16x32_bf16 v[86:89], v[134:137], v[174:177], v[86:89]
	v_mfma_f32_16x16x32_bf16 v[82:85], v[142:145], v[174:177], v[82:85]
	s_setprio 0
	s_barrier
	s_add_i32 s30, 0, 0x1c000
	s_add_i32 s31, s57, s38
	v_add_u32_e32 v190, s30, v216
	v_lshl_add_u64 v[208:209], v[208:209], 0, s[66:67]
	s_mov_b32 m0, s31
	ds_read_b128 v[178:181], v190
	ds_read_b128 v[182:185], v190 offset:1024
	ds_read_b128 v[186:189], v190 offset:2048
	ds_read_b128 v[190:193], v190 offset:3072
	global_load_lds_dwordx4 v[208:209], off
	v_lshl_add_u64 v[208:209], v[210:211], 0, s[66:67]
	s_add_i32 m0, s31, 0x2000
	s_nop 0
	global_load_lds_dwordx4 v[208:209], off
	s_barrier
	s_waitcnt lgkmcnt(0)
	s_setprio 1
	s_waitcnt lgkmcnt(0)
	v_mfma_f32_16x16x32_bf16 v[110:113], v[178:181], v[146:149], v[110:113]
	v_mfma_f32_16x16x32_bf16 v[106:109], v[186:189], v[146:149], v[106:109]
	v_mfma_f32_16x16x32_bf16 v[94:97], v[178:181], v[154:157], v[94:97]
	v_mfma_f32_16x16x32_bf16 v[90:93], v[186:189], v[154:157], v[90:93]
	v_mfma_f32_16x16x32_bf16 v[78:81], v[178:181], v[162:165], v[78:81]
	v_mfma_f32_16x16x32_bf16 v[74:77], v[186:189], v[162:165], v[74:77]
	v_mfma_f32_16x16x32_bf16 v[70:73], v[178:181], v[170:173], v[70:73]
	v_mfma_f32_16x16x32_bf16 v[66:69], v[186:189], v[170:173], v[66:69]
	v_mfma_f32_16x16x32_bf16 v[110:113], v[182:185], v[150:153], v[110:113]
	v_mfma_f32_16x16x32_bf16 v[106:109], v[190:193], v[150:153], v[106:109]
	v_mfma_f32_16x16x32_bf16 v[94:97], v[182:185], v[158:161], v[94:97]
	v_mfma_f32_16x16x32_bf16 v[90:93], v[190:193], v[158:161], v[90:93]
	v_mfma_f32_16x16x32_bf16 v[78:81], v[182:185], v[166:169], v[78:81]
	v_mfma_f32_16x16x32_bf16 v[74:77], v[190:193], v[166:169], v[74:77]
	v_mfma_f32_16x16x32_bf16 v[70:73], v[182:185], v[174:177], v[70:73]
	v_mfma_f32_16x16x32_bf16 v[66:69], v[190:193], v[174:177], v[66:69]
	s_setprio 0
	s_mov_b32 m0, s49
	v_lshl_add_u64 v[208:209], v[212:213], 0, s[66:67]
	s_barrier
	ds_read_b128 v[146:149], v217 offset:49152
	ds_read_b128 v[150:153], v217 offset:50176
	ds_read_b128 v[154:157], v217 offset:51200
	ds_read_b128 v[158:161], v217 offset:52224
	ds_read_b128 v[162:165], v217 offset:53248
	ds_read_b128 v[166:169], v217 offset:54272
	ds_read_b128 v[170:173], v217 offset:55296
	ds_read_b128 v[174:177], v217 offset:56320
	global_load_lds_dwordx4 v[208:209], off
	v_lshl_add_u64 v[208:209], v[218:219], 0, s[66:67]
	s_mov_b32 m0, s50
	s_nop 0
	global_load_lds_dwordx4 v[208:209], off
	s_barrier
	s_waitcnt lgkmcnt(0)
	s_setprio 1
	s_waitcnt lgkmcnt(0)
	v_mfma_f32_16x16x32_bf16 v[62:65], v[130:133], v[146:149], v[62:65]
	v_mfma_f32_16x16x32_bf16 v[58:61], v[138:141], v[146:149], v[58:61]
	v_mfma_f32_16x16x32_bf16 v[54:57], v[130:133], v[154:157], v[54:57]
	v_mfma_f32_16x16x32_bf16 v[50:53], v[138:141], v[154:157], v[50:53]
	v_mfma_f32_16x16x32_bf16 v[36:39], v[130:133], v[162:165], v[36:39]
	v_mfma_f32_16x16x32_bf16 v[32:35], v[138:141], v[162:165], v[32:35]
	v_mfma_f32_16x16x32_bf16 v[20:23], v[130:133], v[170:173], v[20:23]
	v_mfma_f32_16x16x32_bf16 v[16:19], v[138:141], v[170:173], v[16:19]
	v_mfma_f32_16x16x32_bf16 v[62:65], v[134:137], v[150:153], v[62:65]
	v_mfma_f32_16x16x32_bf16 v[58:61], v[142:145], v[150:153], v[58:61]
	v_mfma_f32_16x16x32_bf16 v[54:57], v[134:137], v[158:161], v[54:57]
	v_mfma_f32_16x16x32_bf16 v[50:53], v[142:145], v[158:161], v[50:53]
	v_mfma_f32_16x16x32_bf16 v[36:39], v[134:137], v[166:169], v[36:39]
	v_mfma_f32_16x16x32_bf16 v[32:35], v[142:145], v[166:169], v[32:35]
	v_mfma_f32_16x16x32_bf16 v[20:23], v[134:137], v[174:177], v[20:23]
	v_mfma_f32_16x16x32_bf16 v[16:19], v[142:145], v[174:177], v[16:19]
	s_setprio 0
	s_barrier
	s_add_u32 s28, s28, 0x40080
	s_addc_u32 s29, s29, 0
	s_add_i32 s30, s30, s38
	v_lshl_add_u64 v[130:131], s[28:29], 0, v[48:49]
	s_mov_b32 m0, s30
	s_nop 0
	global_load_lds_dwordx4 v[130:131], off
	v_lshl_add_u64 v[130:131], s[28:29], 0, v[202:203]
	s_add_i32 m0, s30, 0x2000
	s_nop 0
	global_load_lds_dwordx4 v[130:131], off
	s_waitcnt vmcnt(6)
	s_barrier
	s_setprio 1
	v_mfma_f32_16x16x32_bf16 v[44:47], v[178:181], v[146:149], v[44:47]
	v_mfma_f32_16x16x32_bf16 v[40:43], v[186:189], v[146:149], v[40:43]
	v_mfma_f32_16x16x32_bf16 v[28:31], v[178:181], v[154:157], v[28:31]
	v_mfma_f32_16x16x32_bf16 v[24:27], v[186:189], v[154:157], v[24:27]
	v_mfma_f32_16x16x32_bf16 v[12:15], v[178:181], v[162:165], v[12:15]
	v_mfma_f32_16x16x32_bf16 v[8:11], v[186:189], v[162:165], v[8:11]
	v_mfma_f32_16x16x32_bf16 v[4:7], v[178:181], v[170:173], v[4:7]
	v_mfma_f32_16x16x32_bf16 v[0:3], v[186:189], v[170:173], v[0:3]
	v_mfma_f32_16x16x32_bf16 v[44:47], v[182:185], v[150:153], v[44:47]
	v_mfma_f32_16x16x32_bf16 v[40:43], v[190:193], v[150:153], v[40:43]
	v_mfma_f32_16x16x32_bf16 v[28:31], v[182:185], v[158:161], v[28:31]
	v_mfma_f32_16x16x32_bf16 v[24:27], v[190:193], v[158:161], v[24:27]
	v_mfma_f32_16x16x32_bf16 v[12:15], v[182:185], v[166:169], v[12:15]
	v_mfma_f32_16x16x32_bf16 v[8:11], v[190:193], v[166:169], v[8:11]
	v_mfma_f32_16x16x32_bf16 v[4:7], v[182:185], v[174:177], v[4:7]
	v_mfma_f32_16x16x32_bf16 v[0:3], v[190:193], v[174:177], v[0:3]
	s_setprio 0
	s_add_u32 s24, s24, 0x100
	s_addc_u32 s25, s25, 0
	s_add_u32 s19, s19, 0x100
	s_addc_u32 s27, s27, 0
	s_cmp_ge_i32 s56, s1
	s_mov_b32 s28, s56
	s_barrier
	s_cbranch_scc0 .LBB0_1056
	v_mov_b32_e32 v130, v214
	v_mov_b32_e32 v131, v215
	s_bitcmp1_b32 s55, 0
	v_add_u32_e32 v134, s47, v130
	v_lshlrev_b32_e32 v130, 8, v134
	v_lshl_add_u32 v132, v131, 3, s48
	v_ashrrev_i32_e32 v131, 31, v130
	v_lshl_add_u64 v[130:131], v[130:131], 1, s[12:13]
	v_ashrrev_i32_e32 v133, 31, v132
	s_cselect_b64 s[28:29], -1, 0
	v_lshlrev_b32_e32 v208, 9, v215
	v_lshl_add_u32 v208, v214, 4, v208
	v_lshl_add_u32 v208, s47, 9, v208
	v_lshl_add_u32 v208, s48, 6, v208
	v_mov_b32_e32 v209, 0
	v_lshl_add_u64 v[208:209], v[208:209], 0, s[12:13]
	s_mov_b64 s[24:25], -1
	s_and_b64 vcc, exec, s[28:29]
	s_mov_b32 s57, s81
	s_cbranch_vccz .LBB0_1093
	s_mov_b64 s[24:25], 0x20000
	v_lshl_add_u64 v[130:131], v[208:209], 0, s[24:25]
	s_and_b32 s1, s55, -2
	s_mov_b64 s[24:25], 0x100
	s_cmp_lg_u32 s1, 4
	v_mov_b64_e32 v[210:211], v[130:131]
	s_cbranch_scc1 .LBB0_1060
	v_lshl_add_u32 v134, s26, 8, v134
	v_ashrrev_i32_e32 v135, 31, v134
	v_lshlrev_b64 v[134:135], 11, v[134:135]
	s_lshl_b32 s0, s0, 8
	v_lshl_add_u64 v[134:135], s[14:15], 0, v[134:135]
	s_ashr_i32 s1, s0, 31
	v_lshl_add_u64 v[134:135], s[0:1], 1, v[134:135]
	v_lshl_add_u64 v[210:211], v[132:133], 1, v[134:135]
	s_mov_b64 s[24:25], 0x400
